# hgrn_sample_unit: state stores without the nontemporal hint (store acknowledgement latency between the two units of a workgroup)
# baseline (speedup 1.0000x reference)
.LBB0_323:
	s_ashr_i32 s10, s16, 2
	s_add_i32 s6, s10, 0x4000
	s_and_b32 s7, s16, 3
	s_mul_i32 s0, s6, 0xc00
	v_mov_b32_e32 v5, v176
	s_mul_hi_i32 s1, s6, 0xc00
	s_add_u32 s0, s82, s0
	s_addc_u32 s1, s83, s1
	v_and_b32_e32 v3, 0x7f, v5
	s_lshl_b32 s12, s7, 7
	s_mul_i32 s8, s6, 0x2600
	s_mul_hi_i32 s9, s6, 0x2600
	s_add_u32 s8, s80, s8
	v_or_b32_e32 v0, s12, v3
	s_addc_u32 s9, s81, s9
	v_lshlrev_b32_e32 v4, 1, v0
	global_load_ushort v0, v4, s[8:9]
	v_readlane_b32 s11, v254, 63
	v_ashrrev_i32_e32 v10, 2, v5
	v_and_b32_e32 v6, 0xffffffe0, v10
	v_ashrrev_i32_e32 v7, 31, v6
	v_lshlrev_b64 v[12:13], 9, v[6:7]
	s_waitcnt vmcnt(0)
	v_lshlrev_b32_e32 v8, 16, v0
	v_mov_b32_e32 v0, s11
	ds_read_b64 v[0:1], v0
	s_ashr_i32 s11, s10, 31
	s_lshl_b64 s[10:11], s[10:11], 2
	s_add_u32 s10, s10, s2
	s_addc_u32 s11, s11, s3
	s_or_b32 s10, s10, s7
	s_waitcnt lgkmcnt(0)
	v_readfirstlane_b32 s13, v0
	s_lshl_b64 s[10:11], s[10:11], 16
	v_readfirstlane_b32 s15, v1
	s_add_u32 s14, s13, s10
	s_addc_u32 s15, s15, s11
	v_readlane_b32 s13, v253, 16
	v_lshl_add_u64 v[14:15], s[14:15], 0, v[12:13]
	v_lshlrev_b32_e32 v0, 2, v3
	v_mov_b32_e32 v1, v2
	s_add_u32 s10, s13, s10
	v_readlane_b32 s13, v253, 17
	v_lshl_add_u64 v[34:35], v[14:15], 0, v[0:1]
	s_addc_u32 s11, s13, s11
	v_lshl_add_u64 v[36:37], s[10:11], 0, v[12:13]
	v_add_co_u32_e32 v12, vcc, s20, v34
	s_lshl_b32 s10, s7, 9
	s_nop 0
	v_addc_co_u32_e32 v13, vcc, 0, v35, vcc
	v_add_co_u32_e32 v38, vcc, s95, v34
	flat_load_dword v32, v[34:35] nt
	flat_load_dword v42, v[34:35] offset:512 nt
	flat_load_dword v43, v[34:35] offset:1024 nt
	flat_load_dword v44, v[34:35] offset:1536 nt
	flat_load_dword v45, v[34:35] offset:2048 nt
	flat_load_dword v46, v[34:35] offset:2560 nt
	flat_load_dword v47, v[34:35] offset:3072 nt
	flat_load_dword v48, v[34:35] offset:3584 nt
	v_addc_co_u32_e32 v39, vcc, 0, v35, vcc
	v_add_co_u32_e32 v34, vcc, s78, v34
	s_add_u32 s0, s0, s10
	s_nop 0
	v_addc_co_u32_e32 v35, vcc, 0, v35, vcc
	s_addc_u32 s1, s1, 0
	flat_load_dword v49, v[12:13] nt
	flat_load_dword v30, v[12:13] offset:512 nt
	flat_load_dword v28, v[12:13] offset:1024 nt
	flat_load_dword v26, v[12:13] offset:1536 nt
	flat_load_dword v24, v[12:13] offset:2048 nt
	flat_load_dword v22, v[12:13] offset:2560 nt
	flat_load_dword v20, v[12:13] offset:3072 nt
	flat_load_dword v18, v[12:13] offset:3584 nt
	flat_load_dword v16, v[38:39] nt
	flat_load_dword v14, v[38:39] offset:512 nt
	s_nop 0
	flat_load_dword v12, v[38:39] offset:1024 nt
	flat_load_dword v9, v[38:39] offset:1536 nt
	flat_load_dword v33, v[38:39] offset:2048 nt
	flat_load_dword v31, v[38:39] offset:2560 nt
	flat_load_dword v29, v[38:39] offset:3072 nt
	flat_load_dword v27, v[38:39] offset:3584 nt
	flat_load_dword v25, v[34:35] nt
	flat_load_dword v23, v[34:35] offset:512 nt
	flat_load_dword v21, v[34:35] offset:1024 nt
	flat_load_dword v19, v[34:35] offset:1536 nt
	flat_load_dword v17, v[34:35] offset:2048 nt
	flat_load_dword v15, v[34:35] offset:2560 nt
	flat_load_dword v13, v[34:35] offset:3072 nt
	flat_load_dword v11, v[34:35] offset:3584 nt
	v_lshl_add_u64 v[34:35], v[6:7], 2, s[0:1]
	v_lshl_add_u64 v[36:37], v[36:37], 0, v[0:1]
	global_load_dwordx4 v[96:99], v[34:35], off
	global_load_dwordx4 v[100:103], v[34:35], off offset:16
	global_load_dwordx4 v[104:107], v[34:35], off offset:32
	global_load_dwordx4 v[108:111], v[34:35], off offset:48
	global_load_dwordx4 v[112:115], v[34:35], off offset:64
	global_load_dwordx4 v[116:119], v[34:35], off offset:80
	global_load_dwordx4 v[120:123], v[34:35], off offset:96
	global_load_dwordx4 v[124:127], v[34:35], off offset:112
	s_lshl_b32 s7, s7, 8
	s_sub_u32 s7, 0, s7
	s_subb_u32 s11, 0, 0
	s_add_u32 s10, s0, s7
	s_addc_u32 s11, s1, s11
	v_lshl_add_u64 v[6:7], v[6:7], 1, s[10:11]
	global_load_dwordx4 v[128:131], v[6:7], off offset:2048
	global_load_dwordx4 v[132:135], v[6:7], off offset:2064
	global_load_dwordx4 v[136:139], v[6:7], off offset:2080
	global_load_dwordx4 v[140:143], v[6:7], off offset:2096
	v_add_co_u32_e32 v52, vcc, s20, v36
	s_nop 1
	v_addc_co_u32_e32 v53, vcc, 0, v37, vcc
	v_add_co_u32_e32 v54, vcc, s95, v36
	s_nop 1
	v_addc_co_u32_e32 v55, vcc, 0, v37, vcc
	v_add_co_u32_e32 v56, vcc, s78, v36
	s_nop 1
	v_addc_co_u32_e32 v57, vcc, 0, v37, vcc
	s_waitcnt vmcnt(0) lgkmcnt(0)
	v_sub_f32_e32 v58, 1.0, v96
	v_mul_f32_e32 v32, v32, v58
	v_fmac_f32_e32 v32, v96, v8
	global_store_dword v[36:37], v32, off
	v_lshlrev_b32_e32 v59, 16, v128
	v_mul_f32_e32 v1, v32, v59
	v_sub_f32_e32 v60, 1.0, v97
	v_mul_f32_e32 v42, v42, v60
	v_fmac_f32_e32 v42, v97, v8
	global_store_dword v[36:37], v42, off offset:512
	v_and_b32_e32 v61, 0xffff0000, v128
	v_fmac_f32_e32 v1, v42, v61
	v_sub_f32_e32 v58, 1.0, v98
	v_mul_f32_e32 v43, v43, v58
	v_fmac_f32_e32 v43, v98, v8
	global_store_dword v[36:37], v43, off offset:1024
	v_lshlrev_b32_e32 v59, 16, v129
	v_fmac_f32_e32 v1, v43, v59
	v_sub_f32_e32 v60, 1.0, v99
	v_mul_f32_e32 v44, v44, v60
	v_fmac_f32_e32 v44, v99, v8
	global_store_dword v[36:37], v44, off offset:1536
	v_and_b32_e32 v61, 0xffff0000, v129
	v_fmac_f32_e32 v1, v44, v61
	v_sub_f32_e32 v58, 1.0, v100
	v_mul_f32_e32 v45, v45, v58
	v_fmac_f32_e32 v45, v100, v8
	global_store_dword v[36:37], v45, off offset:2048
	v_lshlrev_b32_e32 v59, 16, v130
	v_fmac_f32_e32 v1, v45, v59
	v_sub_f32_e32 v60, 1.0, v101
	v_mul_f32_e32 v46, v46, v60
	v_fmac_f32_e32 v46, v101, v8
	global_store_dword v[36:37], v46, off offset:2560
	v_and_b32_e32 v61, 0xffff0000, v130
	v_fmac_f32_e32 v1, v46, v61
	v_sub_f32_e32 v58, 1.0, v102
	v_mul_f32_e32 v47, v47, v58
	v_fmac_f32_e32 v47, v102, v8
	global_store_dword v[36:37], v47, off offset:3072
	v_lshlrev_b32_e32 v59, 16, v131
	v_fmac_f32_e32 v1, v47, v59
	v_sub_f32_e32 v60, 1.0, v103
	v_mul_f32_e32 v48, v48, v60
	v_fmac_f32_e32 v48, v103, v8
	global_store_dword v[36:37], v48, off offset:3584
	v_and_b32_e32 v61, 0xffff0000, v131
	v_fmac_f32_e32 v1, v48, v61
	v_sub_f32_e32 v58, 1.0, v104
	v_mul_f32_e32 v49, v49, v58
	v_fmac_f32_e32 v49, v104, v8
	global_store_dword v[52:53], v49, off
	v_lshlrev_b32_e32 v59, 16, v132
	v_fmac_f32_e32 v1, v49, v59
	v_sub_f32_e32 v60, 1.0, v105
	v_mul_f32_e32 v30, v30, v60
	v_fmac_f32_e32 v30, v105, v8
	global_store_dword v[52:53], v30, off offset:512
	v_and_b32_e32 v61, 0xffff0000, v132
	v_fmac_f32_e32 v1, v30, v61
	v_sub_f32_e32 v58, 1.0, v106
	v_mul_f32_e32 v28, v28, v58
	v_fmac_f32_e32 v28, v106, v8
	global_store_dword v[52:53], v28, off offset:1024
	v_lshlrev_b32_e32 v59, 16, v133
	v_fmac_f32_e32 v1, v28, v59
	v_sub_f32_e32 v60, 1.0, v107
	v_mul_f32_e32 v26, v26, v60
	v_fmac_f32_e32 v26, v107, v8
	global_store_dword v[52:53], v26, off offset:1536
	v_and_b32_e32 v61, 0xffff0000, v133
	v_fmac_f32_e32 v1, v26, v61
	v_sub_f32_e32 v58, 1.0, v108
	v_mul_f32_e32 v24, v24, v58
	v_fmac_f32_e32 v24, v108, v8
	global_store_dword v[52:53], v24, off offset:2048
	v_lshlrev_b32_e32 v59, 16, v134
	v_fmac_f32_e32 v1, v24, v59
	v_sub_f32_e32 v60, 1.0, v109
	v_mul_f32_e32 v22, v22, v60
	v_fmac_f32_e32 v22, v109, v8
	global_store_dword v[52:53], v22, off offset:2560
	v_and_b32_e32 v61, 0xffff0000, v134
	v_fmac_f32_e32 v1, v22, v61
	v_sub_f32_e32 v58, 1.0, v110
	v_mul_f32_e32 v20, v20, v58
	v_fmac_f32_e32 v20, v110, v8
	global_store_dword v[52:53], v20, off offset:3072
	v_lshlrev_b32_e32 v59, 16, v135
	v_fmac_f32_e32 v1, v20, v59
	v_sub_f32_e32 v60, 1.0, v111
	v_mul_f32_e32 v18, v18, v60
	v_fmac_f32_e32 v18, v111, v8
	global_store_dword v[52:53], v18, off offset:3584
	v_and_b32_e32 v61, 0xffff0000, v135
	v_fmac_f32_e32 v1, v18, v61
	v_sub_f32_e32 v58, 1.0, v112
	v_mul_f32_e32 v16, v16, v58
	v_fmac_f32_e32 v16, v112, v8
	global_store_dword v[54:55], v16, off
	v_lshlrev_b32_e32 v59, 16, v136
	v_fmac_f32_e32 v1, v16, v59
	v_sub_f32_e32 v60, 1.0, v113
	v_mul_f32_e32 v14, v14, v60
	v_fmac_f32_e32 v14, v113, v8
	global_store_dword v[54:55], v14, off offset:512
	v_and_b32_e32 v61, 0xffff0000, v136
	v_fmac_f32_e32 v1, v14, v61
	v_sub_f32_e32 v58, 1.0, v114
	v_mul_f32_e32 v12, v12, v58
	v_fmac_f32_e32 v12, v114, v8
	global_store_dword v[54:55], v12, off offset:1024
	v_lshlrev_b32_e32 v59, 16, v137
	v_fmac_f32_e32 v1, v12, v59
	v_sub_f32_e32 v60, 1.0, v115
	v_mul_f32_e32 v9, v9, v60
	v_fmac_f32_e32 v9, v115, v8
	global_store_dword v[54:55], v9, off offset:1536
	v_and_b32_e32 v61, 0xffff0000, v137
	v_fmac_f32_e32 v1, v9, v61
	v_sub_f32_e32 v58, 1.0, v116
	v_mul_f32_e32 v33, v33, v58
	v_fmac_f32_e32 v33, v116, v8
	global_store_dword v[54:55], v33, off offset:2048
	v_lshlrev_b32_e32 v59, 16, v138
	v_fmac_f32_e32 v1, v33, v59
	v_sub_f32_e32 v60, 1.0, v117
	v_mul_f32_e32 v31, v31, v60
	v_fmac_f32_e32 v31, v117, v8
	global_store_dword v[54:55], v31, off offset:2560
	v_and_b32_e32 v61, 0xffff0000, v138
	v_fmac_f32_e32 v1, v31, v61
	v_sub_f32_e32 v58, 1.0, v118
	v_mul_f32_e32 v29, v29, v58
	v_fmac_f32_e32 v29, v118, v8
	global_store_dword v[54:55], v29, off offset:3072
	v_lshlrev_b32_e32 v59, 16, v139
	v_fmac_f32_e32 v1, v29, v59
	v_sub_f32_e32 v60, 1.0, v119
	v_mul_f32_e32 v27, v27, v60
	v_fmac_f32_e32 v27, v119, v8
	global_store_dword v[54:55], v27, off offset:3584
	v_and_b32_e32 v61, 0xffff0000, v139
	v_fmac_f32_e32 v1, v27, v61
	v_sub_f32_e32 v58, 1.0, v120
	v_mul_f32_e32 v25, v25, v58
	v_fmac_f32_e32 v25, v120, v8
	global_store_dword v[56:57], v25, off
	v_lshlrev_b32_e32 v59, 16, v140
	v_fmac_f32_e32 v1, v25, v59
	v_sub_f32_e32 v60, 1.0, v121
	v_mul_f32_e32 v23, v23, v60
	v_fmac_f32_e32 v23, v121, v8
	global_store_dword v[56:57], v23, off offset:512
	v_and_b32_e32 v61, 0xffff0000, v140
	v_fmac_f32_e32 v1, v23, v61
	v_sub_f32_e32 v58, 1.0, v122
	v_mul_f32_e32 v21, v21, v58
	v_fmac_f32_e32 v21, v122, v8
	global_store_dword v[56:57], v21, off offset:1024
	v_lshlrev_b32_e32 v59, 16, v141
	v_fmac_f32_e32 v1, v21, v59
	v_sub_f32_e32 v60, 1.0, v123
	v_mul_f32_e32 v19, v19, v60
	v_fmac_f32_e32 v19, v123, v8
	global_store_dword v[56:57], v19, off offset:1536
	v_and_b32_e32 v61, 0xffff0000, v141
	v_fmac_f32_e32 v1, v19, v61
	v_sub_f32_e32 v58, 1.0, v124
	v_mul_f32_e32 v17, v17, v58
	v_fmac_f32_e32 v17, v124, v8
	global_store_dword v[56:57], v17, off offset:2048
	v_lshlrev_b32_e32 v59, 16, v142
	v_fmac_f32_e32 v1, v17, v59
	v_sub_f32_e32 v60, 1.0, v125
	v_mul_f32_e32 v15, v15, v60
	v_fmac_f32_e32 v15, v125, v8
	global_store_dword v[56:57], v15, off offset:2560
	v_and_b32_e32 v61, 0xffff0000, v142
	v_fmac_f32_e32 v1, v15, v61
	v_sub_f32_e32 v58, 1.0, v126
	v_mul_f32_e32 v13, v13, v58
	v_fmac_f32_e32 v13, v126, v8
	global_store_dword v[56:57], v13, off offset:3072
	v_lshlrev_b32_e32 v59, 16, v143
	v_fmac_f32_e32 v1, v13, v59
	v_sub_f32_e32 v60, 1.0, v127
	v_mul_f32_e32 v11, v11, v60
	v_fmac_f32_e32 v11, v127, v8
	global_store_dword v[56:57], v11, off offset:3584
	v_and_b32_e32 v61, 0xffff0000, v143
	v_fmac_f32_e32 v1, v11, v61
	s_movk_i32 s0, 0x80
	v_cmp_gt_i32_e32 vcc, s0, v5
	v_lshl_add_u32 v6, v5, 2, 0
	s_barrier
	ds_write_b32 v6, v1
	s_waitcnt lgkmcnt(0)
	s_barrier
	s_and_saveexec_b64 s[10:11], vcc
	s_cbranch_execz .LBB0_325
	v_lshl_add_u32 v1, v3, 2, 0
	ds_read2st64_b32 v[6:7], v1 offset1:2
	ds_read2st64_b32 v[8:9], v1 offset0:4 offset1:6
	v_cmp_lt_i32_e64 s[0:1], v182, v181
	v_ashrrev_i32_e32 v5, 6, v5
	v_lshl_add_u32 v5, v5, 2, 0
	s_waitcnt lgkmcnt(1)
	v_mov_b32_e32 v10, v6
	s_waitcnt lgkmcnt(0)
	v_mov_b32_e32 v11, v8
	v_mov_b32_e32 v8, v7
	v_pk_add_f32 v[6:7], v[10:11], v[8:9]
	s_nop 0
	v_add_f32_e32 v1, v6, v7
	v_cndmask_b32_e64 v7, v179, v182, s[0:1]
	v_mul_f32_e32 v6, v1, v1
	v_lshlrev_b32_e32 v7, 2, v7
	ds_bpermute_b32 v6, v7, v6
	v_cmp_lt_i32_e64 s[0:1], v183, v181
	s_waitcnt lgkmcnt(0)
	v_fmac_f32_e32 v6, v1, v1
	v_cndmask_b32_e64 v7, v179, v183, s[0:1]
	v_lshlrev_b32_e32 v1, 2, v7
	ds_bpermute_b32 v1, v1, v6
	v_cmp_lt_i32_e64 s[0:1], v184, v181
	s_waitcnt lgkmcnt(0)
	v_add_f32_e32 v1, v6, v1
	v_cndmask_b32_e64 v7, v179, v184, s[0:1]
	v_lshlrev_b32_e32 v7, 2, v7
	ds_bpermute_b32 v6, v7, v1
	v_cmp_lt_i32_e64 s[0:1], v185, v181
	s_waitcnt lgkmcnt(0)
	v_add_f32_e32 v1, v1, v6
	v_cndmask_b32_e64 v7, v179, v185, s[0:1]
	v_lshlrev_b32_e32 v7, 2, v7
	ds_bpermute_b32 v6, v7, v1
	v_cmp_lt_i32_e64 s[0:1], v186, v181
	s_waitcnt lgkmcnt(0)
	v_add_f32_e32 v1, v1, v6
	v_cndmask_b32_e64 v7, v179, v186, s[0:1]
	v_lshlrev_b32_e32 v7, 2, v7
	ds_bpermute_b32 v6, v7, v1
	v_cmp_lt_i32_e64 s[0:1], v187, v181
	s_waitcnt lgkmcnt(0)
	v_add_f32_e32 v1, v1, v6
	v_cndmask_b32_e64 v7, v179, v187, s[0:1]
	v_lshlrev_b32_e32 v7, 2, v7
	ds_bpermute_b32 v6, v7, v1
	s_waitcnt lgkmcnt(0)
	v_add_f32_e32 v1, v1, v6
	ds_write_b32 v5, v1 offset:2048
